# sample diff-attention item (phase 2): finalize gain loads and the new-keys V loads issued together with counted waits
# baseline (speedup 1.0000x reference)
.LBB0_880:
	s_or_b64 exec, exec, s[0:1]
	v_mad_u64_u32 v[36:37], s[0:1], v36, s29, v[40:41]
	s_waitcnt vmcnt(0)
	ds_write_b128 v36, v[32:35]
	v_or_b32_e32 v32, s6, v107
	v_ashrrev_i32_e32 v33, 31, v32
	v_lshlrev_b64 v[32:33], 13, v[32:33]
	v_lshl_add_u64 v[32:33], s[10:11], 0, v[32:33]
	s_lshl_b32 s14, s8, 2
	v_lshl_add_u64 v[32:33], v[32:33], 0, s[14:15]
	v_lshl_add_u64 v[48:49], v[116:117], 2, v[32:33]
	global_load_dwordx4 v[32:35], v[48:49], off offset:48
	global_load_dwordx4 v[36:39], v[48:49], off offset:32
	global_load_dwordx4 v[40:43], v[48:49], off offset:16
	global_load_dwordx4 v[44:47], v[48:49], off
	global_load_dwordx4 v[140:143], v[48:49], off offset:112
	global_load_dwordx4 v[144:147], v[48:49], off offset:96
	global_load_dwordx4 v[148:151], v[48:49], off offset:80
	global_load_dwordx4 v[152:155], v[48:49], off offset:64
	v_cmp_lt_u32_e32 vcc, 15, v122
	s_lshl_b32 s5, s5, 6
	s_waitcnt vmcnt(7)
	v_cndmask_b32_e64 v33, v33, 0, vcc
	s_waitcnt vmcnt(6)
	v_cndmask_b32_e64 v37, v37, 0, vcc
	s_waitcnt vmcnt(5)
	v_cndmask_b32_e64 v41, v41, 0, vcc
	s_waitcnt vmcnt(4)
	v_cndmask_b32_e64 v45, v45, 0, vcc
	v_cndmask_b32_e64 v44, v44, 0, vcc
	v_cndmask_b32_e64 v40, v40, 0, vcc
	v_cndmask_b32_e64 v36, v36, 0, vcc
	v_cndmask_b32_e64 v32, v32, 0, vcc
	v_cndmask_b32_e64 v47, v47, 0, vcc
	v_cndmask_b32_e64 v46, v46, 0, vcc
	v_cvt_pk_bf16_f32 v44, v44, v45
	v_cndmask_b32_e64 v43, v43, 0, vcc
	v_cndmask_b32_e64 v42, v42, 0, vcc
	v_cvt_pk_bf16_f32 v40, v40, v41
	v_cndmask_b32_e64 v39, v39, 0, vcc
	v_cndmask_b32_e64 v38, v38, 0, vcc
	v_cvt_pk_bf16_f32 v36, v36, v37
	v_cndmask_b32_e64 v35, v35, 0, vcc
	v_cndmask_b32_e64 v34, v34, 0, vcc
	v_cvt_pk_bf16_f32 v32, v32, v33
	v_cvt_pk_bf16_f32 v45, v46, v47
	ds_write_b16 v137, v44 offset:33792
	ds_write_b16_d16_hi v137, v44 offset:33936
	ds_write_b16 v137, v45 offset:34080
	ds_write_b16_d16_hi v137, v45 offset:34224
	v_cvt_pk_bf16_f32 v41, v42, v43
	ds_write_b16 v137, v40 offset:34368
	ds_write_b16_d16_hi v137, v40 offset:34512
	ds_write_b16 v137, v41 offset:34656
	ds_write_b16_d16_hi v137, v41 offset:34800
	v_cvt_pk_bf16_f32 v37, v38, v39
	ds_write_b16 v137, v36 offset:34944
	ds_write_b16_d16_hi v137, v36 offset:35088
	ds_write_b16 v137, v37 offset:35232
	ds_write_b16_d16_hi v137, v37 offset:35376
	v_cvt_pk_bf16_f32 v33, v34, v35
	ds_write_b16 v137, v32 offset:35520
	ds_write_b16_d16_hi v137, v32 offset:35664
	ds_write_b16 v137, v33 offset:35808
	ds_write_b16_d16_hi v137, v33 offset:35952
	s_waitcnt vmcnt(3)
	v_cndmask_b32_e64 v143, v143, 0, vcc
	s_waitcnt vmcnt(2)
	v_cndmask_b32_e64 v147, v147, 0, vcc
	s_waitcnt vmcnt(1)
	v_cndmask_b32_e64 v151, v151, 0, vcc
	s_waitcnt vmcnt(0)
	v_cndmask_b32_e64 v155, v155, 0, vcc
	v_cndmask_b32_e64 v154, v154, 0, vcc
	v_cndmask_b32_e64 v153, v153, 0, vcc
	v_cndmask_b32_e64 v152, v152, 0, vcc
	v_cndmask_b32_e64 v150, v150, 0, vcc
	v_cndmask_b32_e64 v149, v149, 0, vcc
	v_cndmask_b32_e64 v148, v148, 0, vcc
	v_cndmask_b32_e64 v146, v146, 0, vcc
	v_cndmask_b32_e64 v145, v145, 0, vcc
	v_cndmask_b32_e64 v144, v144, 0, vcc
	v_cndmask_b32_e64 v142, v142, 0, vcc
	v_cndmask_b32_e64 v141, v141, 0, vcc
	v_cndmask_b32_e64 v140, v140, 0, vcc
	v_cvt_pk_bf16_f32 v152, v152, v153
	v_cvt_pk_bf16_f32 v153, v154, v155
	v_cvt_pk_bf16_f32 v148, v148, v149
	v_cvt_pk_bf16_f32 v149, v150, v151
	v_cvt_pk_bf16_f32 v144, v144, v145
	v_cvt_pk_bf16_f32 v145, v146, v147
	v_cvt_pk_bf16_f32 v140, v140, v141
	v_cvt_pk_bf16_f32 v141, v142, v143
	ds_write_b16 v137, v152 offset:36096
	ds_write_b16_d16_hi v137, v152 offset:36240
	ds_write_b16 v137, v153 offset:36384
	ds_write_b16_d16_hi v137, v153 offset:36528
	ds_write_b16 v137, v148 offset:36672
	ds_write_b16_d16_hi v137, v148 offset:36816
	ds_write_b16 v137, v149 offset:36960
	ds_write_b16_d16_hi v137, v149 offset:37104
	ds_write_b16 v137, v144 offset:37248
	ds_write_b16_d16_hi v137, v144 offset:37392
	ds_write_b16 v137, v145 offset:37536
	ds_write_b16_d16_hi v137, v145 offset:37680
	ds_write_b16 v137, v140 offset:37824
	ds_write_b16_d16_hi v137, v140 offset:37968
	ds_write_b16 v137, v141 offset:38112
	ds_write_b16_d16_hi v137, v141 offset:38256
	s_waitcnt lgkmcnt(0)
	s_barrier
	ds_read_b128 v[32:35], v136
	ds_read_b128 v[36:39], v136 offset:64
	ds_read_b128 v[40:43], v136 offset:128
	ds_read_b128 v[44:47], v136 offset:192
	s_waitcnt lgkmcnt(3)
	v_mfma_f32_16x16x32_bf16 v[0:3], v[32:35], v[0:3], 0
	s_waitcnt lgkmcnt(2)
	v_mfma_f32_16x16x32_bf16 v[0:3], v[36:39], v[4:7], v[0:3]
	s_waitcnt lgkmcnt(1)
	v_mfma_f32_16x16x32_bf16 v[0:3], v[40:43], v[8:11], v[0:3]
	s_waitcnt lgkmcnt(0)
	v_mfma_f32_16x16x32_bf16 v[0:3], v[44:47], v[12:15], v[0:3]
	v_cvt_f32_i32_e32 v4, v135
	s_nop 6
	v_mov_b32_e32 v114, v0
	v_xad_u32 v0, v134, -1, v107
	v_cvt_f32_i32_e32 v0, v0
	v_and_b32_e32 v109, 0x7fffffff, v4
	v_pk_mul_f32 v[4:5], v[114:115], v[108:109]
	v_mov_b32_e32 v114, v1
	v_and_b32_e32 v109, 0x7fffffff, v0
	v_pk_mul_f32 v[0:1], v[114:115], v[108:109]
	v_mov_b32_e32 v114, v2
	v_sub_f32_e32 v6, v0, v1
	v_add_u32_e32 v0, -2, v135
	v_cvt_f32_i32_e32 v0, v0
	v_sub_f32_e32 v4, v4, v5
	v_max_f32_e32 v5, 0xff800000, v4
	v_and_b32_e32 v109, 0x7fffffff, v0
	v_pk_mul_f32 v[0:1], v[114:115], v[108:109]
	v_mov_b32_e32 v114, v3
	v_sub_f32_e32 v2, v0, v1
	v_add_u32_e32 v0, -3, v135
	v_cvt_f32_i32_e32 v0, v0
	v_max3_f32 v5, v5, v6, v2
	v_and_b32_e32 v109, 0x7fffffff, v0
	v_pk_mul_f32 v[0:1], v[114:115], v[108:109]
	s_nop 0
	v_sub_f32_e32 v0, v0, v1
	v_max3_f32 v1, v5, v0, s25
	ds_bpermute_b32 v3, v124, v1
	s_waitcnt lgkmcnt(0)
	v_max_f32_e32 v3, v3, v3
	v_max_f32_e32 v1, v1, v3
	ds_bpermute_b32 v3, v125, v1
	s_waitcnt lgkmcnt(0)
	v_max3_f32 v1, v96, v1, v3
	v_sub_f32_e32 v4, v4, v1
	v_exp_f32_e32 v32, v4
	v_sub_f32_e32 v5, v6, v1
	v_exp_f32_e32 v33, v5
	v_sub_f32_e32 v2, v2, v1
	v_exp_f32_e32 v34, v2
	v_sub_f32_e32 v0, v0, v1
	v_sub_f32_e32 v3, v96, v1
	v_exp_f32_e32 v35, v0
	v_sub_f32_e32 v1, 0xff800000, v1
	v_add_f32_e32 v4, 0, v32
	v_exp_f32_e32 v36, v1
	v_add_f32_e32 v4, v33, v4
	v_add_f32_e32 v2, v34, v4
	v_add_f32_e32 v0, v35, v2
	v_add_f32_e32 v0, v36, v0
	v_add_f32_e32 v0, v36, v0
	v_add_f32_e32 v0, v36, v0
	v_add_f32_e32 v0, v36, v0
	v_add_f32_e32 v0, v36, v0
	v_add_f32_e32 v0, v36, v0
	v_add_f32_e32 v0, v36, v0
	v_add_f32_e32 v0, v36, v0
	v_add_f32_e32 v0, v36, v0
	v_exp_f32_e32 v12, v3
	v_add_f32_e32 v0, v36, v0
	v_add_f32_e32 v0, v36, v0
	v_add_f32_e32 v52, v36, v0
	v_fmac_f32_e32 v52, v97, v12
	v_pk_mul_f32 v[2:3], v[30:31], v[12:13] op_sel_hi:[1,0]
	v_pk_mul_f32 v[0:1], v[28:29], v[12:13] op_sel_hi:[1,0]
	v_pk_mul_f32 v[6:7], v[26:27], v[12:13] op_sel_hi:[1,0]
	v_pk_mul_f32 v[4:5], v[24:25], v[12:13] op_sel_hi:[1,0]
	v_pk_mul_f32 v[10:11], v[22:23], v[12:13] op_sel_hi:[1,0]
	v_pk_mul_f32 v[8:9], v[20:21], v[12:13] op_sel_hi:[1,0]
	v_pk_mul_f32 v[14:15], v[18:19], v[12:13] op_sel_hi:[1,0]
	v_pk_mul_f32 v[12:13], v[16:17], v[12:13] op_sel_hi:[1,0]
	v_cvt_pk_bf16_f32 v16, v32, v33
	v_cvt_pk_bf16_f32 v17, v34, v35
	v_cvt_pk_bf16_f32 v18, v36, v36
	ds_read2_b64 v[20:23], v98 offset0:128 offset1:132
	ds_read2_b64 v[24:27], v99 offset0:160 offset1:164
	ds_read2_b64 v[28:31], v100 offset0:192 offset1:196
	ds_read2_b64 v[32:35], v101 offset0:128 offset1:132
	ds_read2_b64 v[36:39], v98 offset0:136 offset1:140
	ds_read2_b64 v[40:43], v99 offset0:168 offset1:172
	ds_read2_b64 v[44:47], v100 offset0:200 offset1:204
	ds_read2_b64 v[48:51], v101 offset0:136 offset1:140
	v_mov_b32_e32 v19, v18
	s_waitcnt lgkmcnt(7)
	s_nop 0
	v_mfma_f32_16x16x32_bf16 v[0:3], v[20:23], v[16:19], v[0:3]
	s_waitcnt lgkmcnt(6)
	v_mfma_f32_16x16x32_bf16 v[4:7], v[24:27], v[16:19], v[4:7]
	s_waitcnt lgkmcnt(5)
	v_mfma_f32_16x16x32_bf16 v[8:11], v[28:31], v[16:19], v[8:11]
	s_waitcnt lgkmcnt(4)
	v_mfma_f32_16x16x32_bf16 v[12:15], v[32:35], v[16:19], v[12:15]
	v_mov_b32_e32 v16, v18
	v_mov_b32_e32 v17, v18
	s_waitcnt lgkmcnt(3)
	s_nop 0
	v_mfma_f32_16x16x32_bf16 v[0:3], v[36:39], v[16:19], v[0:3]
	s_waitcnt lgkmcnt(2)
	v_mfma_f32_16x16x32_bf16 v[4:7], v[40:43], v[16:19], v[4:7]
	s_waitcnt lgkmcnt(1)
	v_mfma_f32_16x16x32_bf16 v[20:23], v[44:47], v[16:19], v[8:11]
	s_waitcnt lgkmcnt(0)
	v_mfma_f32_16x16x32_bf16 v[16:19], v[48:51], v[16:19], v[12:15]
	s_nop 0
	ds_bpermute_b32 v8, v124, v52
	s_cmp_eq_u32 s4, 0
	s_cselect_b64 s[38:39], -1, 0
	s_waitcnt lgkmcnt(0)
	s_barrier
	v_add_f32_e32 v8, v52, v8
	ds_bpermute_b32 v9, v125, v8
	s_waitcnt lgkmcnt(0)
	v_add_f32_e32 v8, v8, v9
	v_rcp_f32_e32 v24, v8
	s_nop 0
	v_pk_mul_f32 v[12:13], v[2:3], v[24:25] op_sel_hi:[1,0]
	v_pk_mul_f32 v[2:3], v[16:17], v[24:25] op_sel_hi:[1,0]
	v_or_b32_e32 v16, s5, v134
	v_pk_mul_f32 v[14:15], v[0:1], v[24:25] op_sel_hi:[1,0]
	v_pk_mul_f32 v[8:9], v[6:7], v[24:25] op_sel_hi:[1,0]
	v_pk_mul_f32 v[10:11], v[4:5], v[24:25] op_sel_hi:[1,0]
	v_pk_mul_f32 v[4:5], v[22:23], v[24:25] op_sel_hi:[1,0]
	v_pk_mul_f32 v[6:7], v[20:21], v[24:25] op_sel_hi:[1,0]
	v_pk_mul_f32 v[0:1], v[18:19], v[24:25] op_sel_hi:[1,0]
	s_and_b64 vcc, exec, s[38:39]
	v_lshlrev_b32_e32 v17, 2, v107
	v_lshlrev_b32_e32 v18, 6, v16
	s_cbranch_vccnz .LBB0_882
	v_add3_u32 v19, 0, v17, v18
	v_add_u32_e32 v20, 0x400, v19
	ds_write2_b32 v19, v14, v15 offset1:16
	ds_write2_b32 v19, v12, v13 offset0:32 offset1:48
	ds_write2_b32 v20, v10, v11 offset1:16
	ds_write2_b32 v20, v8, v9 offset0:32 offset1:48
	v_add_u32_e32 v20, 0x800, v19
	v_add_u32_e32 v19, 0xc00, v19
	ds_write2_b32 v20, v6, v7 offset1:16
	ds_write2_b32 v20, v4, v5 offset0:32 offset1:48
	ds_write2_b32 v19, v2, v3 offset1:16
	ds_write2_b32 v19, v0, v1 offset0:32 offset1:48

.LBB0_886:
	s_and_b64 vcc, exec, s[0:1]
	s_waitcnt lgkmcnt(0)
	s_barrier
	s_cbranch_vccnz .LBB0_741
	s_add_i32 s0, 0, 0x10000
	v_lshl_add_u64 v[18:19], s[96:97], 0, v[112:113]
	s_mov_b32 s37, s15
	v_lshl_add_u32 v17, v107, 2, s0
	v_lshl_add_u64 v[24:25], v[18:19], 0, s[36:37]
	ds_read2_b32 v[18:19], v17 offset1:16
	ds_read_b32 v17, v17 offset:128
	v_readlane_b32 s36, v253, 37
	v_readlane_b32 s50, v253, 51
	v_readlane_b32 s51, v253, 52
	s_waitcnt lgkmcnt(1)
	v_add_f32_e32 v18, v18, v19
	s_waitcnt lgkmcnt(0)
	v_add_f32_e32 v17, v18, v17
	v_lshl_add_u32 v18, v123, 2, s0
	ds_read_b32 v18, v18
	v_readlane_b32 s37, v253, 38
	v_readlane_b32 s38, v253, 39
	v_readlane_b32 s39, v253, 40
	v_readlane_b32 s40, v253, 41
	s_waitcnt lgkmcnt(0)
	v_add_f32_e32 v17, v17, v18
	v_fmamk_f32 v17, v17, 0x3b800000, v128
	v_cmp_gt_f32_e32 vcc, s26, v17
	v_mul_f32_e32 v18, 0x4b800000, v17
	v_readlane_b32 s41, v253, 42
	v_cndmask_b32_e32 v17, v17, v18, vcc
	v_rsq_f32_e32 v17, v17
	v_readlane_b32 s42, v253, 43
	v_readlane_b32 s43, v253, 44
	v_readlane_b32 s44, v253, 45
	v_mul_f32_e32 v18, 0x45800000, v17
	v_cndmask_b32_e32 v17, v17, v18, vcc
	v_mul_f32_e32 v18, 0x3f4ccccd, v17
	v_ashrrev_i32_e32 v17, 31, v16
	v_lshl_add_u64 v[26:27], v[16:17], 2, s[50:51]
	global_load_dwordx4 v[20:23], v[26:27], off
	global_load_dwordx4 v[140:143], v[26:27], off offset:64
	global_load_dwordx4 v[144:147], v[26:27], off offset:128
	global_load_dwordx4 v[148:151], v[26:27], off offset:192
	v_pk_mul_f32 v[14:15], v[14:15], v[18:19] op_sel_hi:[1,0]
	v_pk_mul_f32 v[12:13], v[12:13], v[18:19] op_sel_hi:[1,0]
	v_pk_mul_f32 v[10:11], v[10:11], v[18:19] op_sel_hi:[1,0]
	v_pk_mul_f32 v[8:9], v[8:9], v[18:19] op_sel_hi:[1,0]
	v_pk_mul_f32 v[6:7], v[6:7], v[18:19] op_sel_hi:[1,0]
	v_pk_mul_f32 v[4:5], v[4:5], v[18:19] op_sel_hi:[1,0]
	v_pk_mul_f32 v[2:3], v[2:3], v[18:19] op_sel_hi:[1,0]
	v_pk_mul_f32 v[0:1], v[0:1], v[18:19] op_sel_hi:[1,0]
	v_readlane_b32 s45, v253, 46
	v_readlane_b32 s46, v253, 47
	v_readlane_b32 s47, v253, 48
	v_readlane_b32 s48, v253, 49
	v_readlane_b32 s49, v253, 50
	s_waitcnt vmcnt(3)
	v_pk_mul_f32 v[12:13], v[22:23], v[12:13]
	v_pk_mul_f32 v[14:15], v[20:21], v[14:15]
	s_nop 0
	v_cvt_pk_bf16_f32 v14, v14, v15
	v_cvt_pk_bf16_f32 v15, v12, v13
	v_lshl_add_u64 v[12:13], v[16:17], 1, v[24:25]
	global_store_dwordx2 v[12:13], v[14:15], off
	s_waitcnt vmcnt(3)
	v_pk_mul_f32 v[8:9], v[142:143], v[8:9]
	v_pk_mul_f32 v[10:11], v[140:141], v[10:11]
	s_nop 0
	v_cvt_pk_bf16_f32 v10, v10, v11
	v_cvt_pk_bf16_f32 v11, v8, v9
	global_store_dwordx2 v[12:13], v[10:11], off offset:32
	s_waitcnt vmcnt(3)
	v_pk_mul_f32 v[4:5], v[146:147], v[4:5]
	v_pk_mul_f32 v[6:7], v[144:145], v[6:7]
	s_nop 0
	v_cvt_pk_bf16_f32 v6, v6, v7
	v_cvt_pk_bf16_f32 v7, v4, v5
	global_store_dwordx2 v[12:13], v[6:7], off offset:64
	s_waitcnt vmcnt(3)
	v_pk_mul_f32 v[0:1], v[150:151], v[0:1]
	v_pk_mul_f32 v[2:3], v[148:149], v[2:3]
	s_nop 0
	v_cvt_pk_bf16_f32 v2, v2, v3
	v_cvt_pk_bf16_f32 v3, v0, v1
	global_store_dwordx2 v[12:13], v[2:3], off offset:96
	s_branch .LBB0_741
